# K-split GEMM final-iteration prefetch masked from phase 2 on (loads 2..15) + all s_setprio removed
# speedup vs baseline: 1.0071x; 1.0071x over previous
.LBB0_424:
	ds_read_b128 v[150:153], v163
	ds_read_b128 v[154:157], v163 offset:1024
	ds_read_b128 v[166:169], v163 offset:2048
	ds_read_b128 v[170:173], v163 offset:3072
	ds_read_b128 v[174:177], v164
	ds_read_b128 v[178:181], v164 offset:1024
	ds_read_b128 v[182:185], v164 offset:2048
	ds_read_b128 v[186:189], v164 offset:3072
	s_add_i32 s25, s24, 2
	s_add_u32 s48, s6, 0xffea0080
	s_addc_u32 s49, s7, -1
	s_cmp_eq_u32 s78, s24
	s_cselect_b32 s51, s74, s49
	s_cselect_b32 s50, s75, s48
	s_cselect_b32 s49, s76, s80
	s_cselect_b32 s48, s77, s79
	s_cselect_b64 s[100:101], s[42:43], -1
	v_lshl_add_u64 v[158:159], s[6:7], 0, v[142:143]
	s_add_i32 m0, s53, 0xc000
	ds_read_b128 v[190:193], v165
	ds_read_b128 v[194:197], v165 offset:1024
	ds_read_b128 v[198:201], v165 offset:2048
	ds_read_b128 v[202:205], v165 offset:3072
	ds_read_b128 v[206:209], v165 offset:4096
	ds_read_b128 v[210:213], v165 offset:5120
	ds_read_b128 v[214:217], v165 offset:6144
	ds_read_b128 v[218:221], v165 offset:7168
	global_load_lds_dwordx4 v[158:159], off
	v_lshl_add_u64 v[158:159], s[6:7], 0, v[144:145]
	s_add_i32 m0, s53, 0xe000
	s_nop 0
	global_load_lds_dwordx4 v[158:159], off
	s_waitcnt vmcnt(8)
	s_waitcnt lgkmcnt(0)
	s_barrier
	s_waitcnt lgkmcnt(0)
	v_mfma_f32_16x16x32_bf16 v[86:89], v[150:153], v[190:193], v[86:89]
	v_mfma_f32_16x16x32_bf16 v[78:81], v[166:169], v[190:193], v[78:81]
	v_mfma_f32_16x16x32_bf16 v[66:69], v[150:153], v[198:201], v[66:69]
	v_mfma_f32_16x16x32_bf16 v[62:65], v[166:169], v[198:201], v[62:65]
	v_mfma_f32_16x16x32_bf16 v[54:57], v[150:153], v[206:209], v[54:57]
	v_mfma_f32_16x16x32_bf16 v[46:49], v[166:169], v[206:209], v[46:49]
	v_mfma_f32_16x16x32_bf16 v[38:41], v[150:153], v[214:217], v[38:41]
	v_mfma_f32_16x16x32_bf16 v[30:33], v[166:169], v[214:217], v[30:33]
	v_mfma_f32_16x16x32_bf16 v[86:89], v[154:157], v[194:197], v[86:89]
	v_mfma_f32_16x16x32_bf16 v[78:81], v[170:173], v[194:197], v[78:81]
	v_mfma_f32_16x16x32_bf16 v[66:69], v[154:157], v[202:205], v[66:69]
	v_mfma_f32_16x16x32_bf16 v[62:65], v[170:173], v[202:205], v[62:65]
	v_mfma_f32_16x16x32_bf16 v[54:57], v[154:157], v[210:213], v[54:57]
	v_mfma_f32_16x16x32_bf16 v[46:49], v[170:173], v[210:213], v[46:49]
	v_mfma_f32_16x16x32_bf16 v[38:41], v[154:157], v[218:221], v[38:41]
	v_mfma_f32_16x16x32_bf16 v[30:33], v[170:173], v[218:221], v[30:33]
	v_mfma_f32_16x16x32_bf16 v[50:53], v[174:177], v[190:193], v[50:53]
	v_mfma_f32_16x16x32_bf16 v[42:45], v[182:185], v[190:193], v[42:45]
	v_mfma_f32_16x16x32_bf16 v[34:37], v[174:177], v[198:201], v[34:37]
	v_mfma_f32_16x16x32_bf16 v[26:29], v[182:185], v[198:201], v[26:29]
	v_mfma_f32_16x16x32_bf16 v[22:25], v[174:177], v[206:209], v[22:25]
	v_mfma_f32_16x16x32_bf16 v[18:21], v[182:185], v[206:209], v[18:21]
	v_mfma_f32_16x16x32_bf16 v[10:13], v[174:177], v[214:217], v[10:13]
	v_mfma_f32_16x16x32_bf16 v[6:9], v[182:185], v[214:217], v[6:9]
	v_mfma_f32_16x16x32_bf16 v[50:53], v[178:181], v[194:197], v[50:53]
	v_mfma_f32_16x16x32_bf16 v[42:45], v[186:189], v[194:197], v[42:45]
	v_mfma_f32_16x16x32_bf16 v[34:37], v[178:181], v[202:205], v[34:37]
	v_mfma_f32_16x16x32_bf16 v[26:29], v[186:189], v[202:205], v[26:29]
	v_mfma_f32_16x16x32_bf16 v[22:25], v[178:181], v[210:213], v[22:25]
	v_mfma_f32_16x16x32_bf16 v[18:21], v[186:189], v[210:213], v[18:21]
	v_mfma_f32_16x16x32_bf16 v[10:13], v[178:181], v[218:221], v[10:13]
	v_mfma_f32_16x16x32_bf16 v[6:9], v[186:189], v[218:221], v[6:9]
	s_barrier
	s_add_i32 s24, s66, s52
	v_lshl_add_u64 v[158:159], s[48:49], 0, v[132:133]
	s_mov_b32 m0, s24
	ds_read_b128 v[190:193], v165 offset:16384
	ds_read_b128 v[194:197], v165 offset:17408
	ds_read_b128 v[198:201], v165 offset:18432
	ds_read_b128 v[202:205], v165 offset:19456
	ds_read_b128 v[206:209], v165 offset:20480
	ds_read_b128 v[210:213], v165 offset:21504
	ds_read_b128 v[214:217], v165 offset:22528
	ds_read_b128 v[218:221], v165 offset:23552
	s_mov_b64 exec, s[100:101]
	global_load_lds_dwordx4 v[158:159], off
	s_mov_b64 exec, -1
	s_add_i32 m0, s24, 0x2000
	s_add_u32 s82, s48, 0x160000
	v_lshl_add_u64 v[222:223], s[48:49], 0, v[136:137]
	s_addc_u32 s83, s49, 0
	s_add_i32 s24, s67, s52
	s_mov_b64 exec, s[100:101]
	global_load_lds_dwordx4 v[222:223], off
	s_mov_b64 exec, -1
	v_lshl_add_u64 v[224:225], s[82:83], 0, v[132:133]
	s_mov_b32 m0, s24
	v_lshl_add_u64 v[226:227], s[50:51], 0, v[134:135]
	s_mov_b64 exec, s[100:101]
	global_load_lds_dwordx4 v[224:225], off
	s_mov_b64 exec, -1
	v_lshl_add_u64 v[224:225], s[82:83], 0, v[136:137]
	s_add_i32 m0, s24, 0x2000
	s_nop 0
	s_mov_b64 exec, s[100:101]
	global_load_lds_dwordx4 v[224:225], off
	s_mov_b64 exec, -1
	v_lshl_add_u64 v[224:225], s[50:51], 0, v[130:131]
	s_mov_b32 m0, s53
	s_nop 0
	s_mov_b64 exec, s[100:101]
	global_load_lds_dwordx4 v[224:225], off
	s_mov_b64 exec, -1
	s_mov_b32 m0, s54
	s_nop 0
	s_mov_b64 exec, s[100:101]
	global_load_lds_dwordx4 v[226:227], off
	s_mov_b64 exec, -1
	s_waitcnt vmcnt(8)
	s_waitcnt lgkmcnt(0)
	s_barrier
	s_waitcnt lgkmcnt(0)
	v_mfma_f32_16x16x32_bf16 v[126:129], v[150:153], v[190:193], v[126:129]
	v_mfma_f32_16x16x32_bf16 v[122:125], v[166:169], v[190:193], v[122:125]
	v_mfma_f32_16x16x32_bf16 v[110:113], v[150:153], v[198:201], v[110:113]
	v_mfma_f32_16x16x32_bf16 v[106:109], v[166:169], v[198:201], v[106:109]
	v_mfma_f32_16x16x32_bf16 v[94:97], v[150:153], v[206:209], v[94:97]
	v_mfma_f32_16x16x32_bf16 v[90:93], v[166:169], v[206:209], v[90:93]
	v_mfma_f32_16x16x32_bf16 v[70:73], v[150:153], v[214:217], v[70:73]
	v_mfma_f32_16x16x32_bf16 v[58:61], v[166:169], v[214:217], v[58:61]
	v_mfma_f32_16x16x32_bf16 v[126:129], v[154:157], v[194:197], v[126:129]
	v_mfma_f32_16x16x32_bf16 v[122:125], v[170:173], v[194:197], v[122:125]
	v_mfma_f32_16x16x32_bf16 v[110:113], v[154:157], v[202:205], v[110:113]
	v_mfma_f32_16x16x32_bf16 v[106:109], v[170:173], v[202:205], v[106:109]
	v_mfma_f32_16x16x32_bf16 v[94:97], v[154:157], v[210:213], v[94:97]
	v_mfma_f32_16x16x32_bf16 v[90:93], v[170:173], v[210:213], v[90:93]
	v_mfma_f32_16x16x32_bf16 v[70:73], v[154:157], v[218:221], v[70:73]
	v_mfma_f32_16x16x32_bf16 v[58:61], v[170:173], v[218:221], v[58:61]
	v_mfma_f32_16x16x32_bf16 v[118:121], v[174:177], v[190:193], v[118:121]
	v_mfma_f32_16x16x32_bf16 v[114:117], v[182:185], v[190:193], v[114:117]
	v_mfma_f32_16x16x32_bf16 v[102:105], v[174:177], v[198:201], v[102:105]
	v_mfma_f32_16x16x32_bf16 v[98:101], v[182:185], v[198:201], v[98:101]
	v_mfma_f32_16x16x32_bf16 v[82:85], v[174:177], v[206:209], v[82:85]
	v_mfma_f32_16x16x32_bf16 v[74:77], v[182:185], v[206:209], v[74:77]
	v_mfma_f32_16x16x32_bf16 v[14:17], v[174:177], v[214:217], v[14:17]
	v_mfma_f32_16x16x32_bf16 v[2:5], v[182:185], v[214:217], v[2:5]
	v_mfma_f32_16x16x32_bf16 v[118:121], v[178:181], v[194:197], v[118:121]
	v_mfma_f32_16x16x32_bf16 v[114:117], v[186:189], v[194:197], v[114:117]
	v_mfma_f32_16x16x32_bf16 v[102:105], v[178:181], v[202:205], v[102:105]
	v_mfma_f32_16x16x32_bf16 v[98:101], v[186:189], v[202:205], v[98:101]
	v_mfma_f32_16x16x32_bf16 v[82:85], v[178:181], v[210:213], v[82:85]
	v_mfma_f32_16x16x32_bf16 v[74:77], v[186:189], v[210:213], v[74:77]
	v_mfma_f32_16x16x32_bf16 v[14:17], v[178:181], v[218:221], v[14:17]
	v_mfma_f32_16x16x32_bf16 v[2:5], v[186:189], v[218:221], v[2:5]
	s_barrier
	s_add_i32 s24, 0, 0x18000
	v_add_u32_e32 v138, s24, v160
	s_add_i32 s81, 0, 0x1c000
	ds_read_b128 v[150:153], v138
	ds_read_b128 v[154:157], v138 offset:1024
	ds_read_b128 v[166:169], v138 offset:2048
	ds_read_b128 v[170:173], v138 offset:3072
	v_add_u32_e32 v138, s81, v160
	ds_read_b128 v[174:177], v138
	ds_read_b128 v[178:181], v138 offset:1024
	ds_read_b128 v[182:185], v138 offset:2048
	ds_read_b128 v[186:189], v138 offset:3072
	s_add_u32 s50, s50, 0x160000
	s_addc_u32 s51, s51, 0
	s_mov_b32 m0, s55
	v_lshl_add_u64 v[228:229], s[50:51], 0, v[130:131]
	ds_read_b128 v[190:193], v165 offset:32768
	ds_read_b128 v[194:197], v165 offset:33792
	ds_read_b128 v[198:201], v165 offset:34816
	ds_read_b128 v[202:205], v165 offset:35840
	ds_read_b128 v[206:209], v165 offset:36864
	ds_read_b128 v[210:213], v165 offset:37888
	ds_read_b128 v[214:217], v165 offset:38912
	ds_read_b128 v[218:221], v165 offset:39936
	s_mov_b64 exec, s[100:101]
	global_load_lds_dwordx4 v[228:229], off
	s_mov_b64 exec, -1
	v_lshl_add_u64 v[228:229], s[50:51], 0, v[134:135]
	s_mov_b32 m0, s56
	s_nop 0
	s_mov_b64 exec, s[100:101]
	global_load_lds_dwordx4 v[228:229], off
	s_mov_b64 exec, -1
	s_waitcnt vmcnt(8)
	s_waitcnt lgkmcnt(0)
	s_barrier
	s_waitcnt lgkmcnt(0)
	v_mfma_f32_16x16x32_bf16 v[86:89], v[150:153], v[190:193], v[86:89]
	v_mfma_f32_16x16x32_bf16 v[78:81], v[166:169], v[190:193], v[78:81]
	v_mfma_f32_16x16x32_bf16 v[66:69], v[150:153], v[198:201], v[66:69]
	v_mfma_f32_16x16x32_bf16 v[62:65], v[166:169], v[198:201], v[62:65]
	v_mfma_f32_16x16x32_bf16 v[54:57], v[150:153], v[206:209], v[54:57]
	v_mfma_f32_16x16x32_bf16 v[46:49], v[166:169], v[206:209], v[46:49]
	v_mfma_f32_16x16x32_bf16 v[38:41], v[150:153], v[214:217], v[38:41]
	v_mfma_f32_16x16x32_bf16 v[30:33], v[166:169], v[214:217], v[30:33]
	v_mfma_f32_16x16x32_bf16 v[86:89], v[154:157], v[194:197], v[86:89]
	v_mfma_f32_16x16x32_bf16 v[78:81], v[170:173], v[194:197], v[78:81]
	v_mfma_f32_16x16x32_bf16 v[66:69], v[154:157], v[202:205], v[66:69]
	v_mfma_f32_16x16x32_bf16 v[62:65], v[170:173], v[202:205], v[62:65]
	v_mfma_f32_16x16x32_bf16 v[54:57], v[154:157], v[210:213], v[54:57]
	v_mfma_f32_16x16x32_bf16 v[46:49], v[170:173], v[210:213], v[46:49]
	v_mfma_f32_16x16x32_bf16 v[38:41], v[154:157], v[218:221], v[38:41]
	v_mfma_f32_16x16x32_bf16 v[30:33], v[170:173], v[218:221], v[30:33]
	v_mfma_f32_16x16x32_bf16 v[50:53], v[174:177], v[190:193], v[50:53]
	v_mfma_f32_16x16x32_bf16 v[42:45], v[182:185], v[190:193], v[42:45]
	v_mfma_f32_16x16x32_bf16 v[34:37], v[174:177], v[198:201], v[34:37]
	v_mfma_f32_16x16x32_bf16 v[26:29], v[182:185], v[198:201], v[26:29]
	v_mfma_f32_16x16x32_bf16 v[22:25], v[174:177], v[206:209], v[22:25]
	v_mfma_f32_16x16x32_bf16 v[18:21], v[182:185], v[206:209], v[18:21]
	v_mfma_f32_16x16x32_bf16 v[10:13], v[174:177], v[214:217], v[10:13]
	v_mfma_f32_16x16x32_bf16 v[6:9], v[182:185], v[214:217], v[6:9]
	v_mfma_f32_16x16x32_bf16 v[50:53], v[178:181], v[194:197], v[50:53]
	v_mfma_f32_16x16x32_bf16 v[42:45], v[186:189], v[194:197], v[42:45]
	v_mfma_f32_16x16x32_bf16 v[34:37], v[178:181], v[202:205], v[34:37]
	v_mfma_f32_16x16x32_bf16 v[26:29], v[186:189], v[202:205], v[26:29]
	v_mfma_f32_16x16x32_bf16 v[22:25], v[178:181], v[210:213], v[22:25]
	v_mfma_f32_16x16x32_bf16 v[18:21], v[186:189], v[210:213], v[18:21]
	v_mfma_f32_16x16x32_bf16 v[10:13], v[178:181], v[218:221], v[10:13]
	v_mfma_f32_16x16x32_bf16 v[6:9], v[186:189], v[218:221], v[6:9]
	s_barrier
	s_add_i32 s24, s24, s52
	v_lshl_add_u64 v[158:159], v[158:159], 0, s[14:15]
	s_mov_b32 m0, s24
	ds_read_b128 v[190:193], v165 offset:49152
	ds_read_b128 v[194:197], v165 offset:50176
	ds_read_b128 v[198:201], v165 offset:51200
	ds_read_b128 v[202:205], v165 offset:52224
	ds_read_b128 v[206:209], v165 offset:53248
	ds_read_b128 v[210:213], v165 offset:54272
	ds_read_b128 v[214:217], v165 offset:55296
	ds_read_b128 v[218:221], v165 offset:56320
	s_mov_b64 exec, s[100:101]
	global_load_lds_dwordx4 v[158:159], off
	s_mov_b64 exec, -1
	s_add_i32 m0, s24, 0x2000
	s_add_u32 s48, s48, 0x160080
	v_lshl_add_u64 v[158:159], v[222:223], 0, s[14:15]
	s_addc_u32 s49, s49, 0
	s_add_i32 s24, s81, s52
	s_mov_b64 exec, s[100:101]
	global_load_lds_dwordx4 v[158:159], off
	s_mov_b64 exec, -1
	v_lshl_add_u64 v[158:159], s[48:49], 0, v[132:133]
	s_mov_b32 m0, s24
	s_nop 0
	s_mov_b64 exec, s[100:101]
	global_load_lds_dwordx4 v[158:159], off
	s_mov_b64 exec, -1
	v_lshl_add_u64 v[158:159], s[48:49], 0, v[136:137]
	s_add_i32 m0, s24, 0x2000
	s_nop 0
	s_mov_b64 exec, s[100:101]
	global_load_lds_dwordx4 v[158:159], off
	s_mov_b64 exec, -1
	v_lshl_add_u64 v[158:159], v[224:225], 0, s[14:15]
	s_mov_b32 m0, s62
	s_nop 0
	s_mov_b64 exec, s[100:101]
	global_load_lds_dwordx4 v[158:159], off
	s_mov_b64 exec, -1
	v_lshl_add_u64 v[158:159], v[226:227], 0, s[14:15]
	s_mov_b32 m0, s63
	s_nop 0
	s_mov_b64 exec, s[100:101]
	global_load_lds_dwordx4 v[158:159], off
	s_mov_b64 exec, -1
	s_waitcnt vmcnt(8)
	s_waitcnt lgkmcnt(0)
	s_barrier
	s_waitcnt lgkmcnt(0)
	v_mfma_f32_16x16x32_bf16 v[126:129], v[150:153], v[190:193], v[126:129]
	v_mfma_f32_16x16x32_bf16 v[122:125], v[166:169], v[190:193], v[122:125]
	v_mfma_f32_16x16x32_bf16 v[110:113], v[150:153], v[198:201], v[110:113]
	v_mfma_f32_16x16x32_bf16 v[106:109], v[166:169], v[198:201], v[106:109]
	v_mfma_f32_16x16x32_bf16 v[94:97], v[150:153], v[206:209], v[94:97]
	v_mfma_f32_16x16x32_bf16 v[90:93], v[166:169], v[206:209], v[90:93]
	v_mfma_f32_16x16x32_bf16 v[70:73], v[150:153], v[214:217], v[70:73]
	v_mfma_f32_16x16x32_bf16 v[58:61], v[166:169], v[214:217], v[58:61]
	v_mfma_f32_16x16x32_bf16 v[126:129], v[154:157], v[194:197], v[126:129]
	v_mfma_f32_16x16x32_bf16 v[122:125], v[170:173], v[194:197], v[122:125]
	v_mfma_f32_16x16x32_bf16 v[110:113], v[154:157], v[202:205], v[110:113]
	v_mfma_f32_16x16x32_bf16 v[106:109], v[170:173], v[202:205], v[106:109]
	v_mfma_f32_16x16x32_bf16 v[94:97], v[154:157], v[210:213], v[94:97]
	v_mfma_f32_16x16x32_bf16 v[90:93], v[170:173], v[210:213], v[90:93]
	v_mfma_f32_16x16x32_bf16 v[70:73], v[154:157], v[218:221], v[70:73]
	v_mfma_f32_16x16x32_bf16 v[58:61], v[170:173], v[218:221], v[58:61]
	v_mfma_f32_16x16x32_bf16 v[118:121], v[174:177], v[190:193], v[118:121]
	v_mfma_f32_16x16x32_bf16 v[114:117], v[182:185], v[190:193], v[114:117]
	v_mfma_f32_16x16x32_bf16 v[102:105], v[174:177], v[198:201], v[102:105]
	v_mfma_f32_16x16x32_bf16 v[98:101], v[182:185], v[198:201], v[98:101]
	v_mfma_f32_16x16x32_bf16 v[82:85], v[174:177], v[206:209], v[82:85]
	v_mfma_f32_16x16x32_bf16 v[74:77], v[182:185], v[206:209], v[74:77]
	v_mfma_f32_16x16x32_bf16 v[14:17], v[174:177], v[214:217], v[14:17]
	v_mfma_f32_16x16x32_bf16 v[2:5], v[182:185], v[214:217], v[2:5]
	v_mfma_f32_16x16x32_bf16 v[118:121], v[178:181], v[194:197], v[118:121]
	v_mfma_f32_16x16x32_bf16 v[114:117], v[186:189], v[194:197], v[114:117]
	v_mfma_f32_16x16x32_bf16 v[102:105], v[178:181], v[202:205], v[102:105]
	v_mfma_f32_16x16x32_bf16 v[98:101], v[186:189], v[202:205], v[98:101]
	v_mfma_f32_16x16x32_bf16 v[82:85], v[178:181], v[210:213], v[82:85]
	v_mfma_f32_16x16x32_bf16 v[74:77], v[186:189], v[210:213], v[74:77]
	v_mfma_f32_16x16x32_bf16 v[14:17], v[178:181], v[218:221], v[14:17]
	v_mfma_f32_16x16x32_bf16 v[2:5], v[186:189], v[218:221], v[2:5]
	s_barrier
	s_add_u32 s6, s6, 0x100
	s_addc_u32 s7, s7, 0
	s_add_u32 s79, s79, 0x100
	s_addc_u32 s80, s80, 0
	s_cmp_ge_i32 s25, s73
	s_mov_b32 s24, s25
	s_cbranch_scc0 .LBB0_424
	s_and_b64 vcc, exec, s[16:17]
	s_cbranch_vccz .LBB0_427
	s_barrier

.LBB0_587:
	ds_read_b128 v[156:159], v152
	ds_read_b128 v[164:167], v152 offset:1024
	ds_read_b128 v[168:171], v152 offset:2048
	ds_read_b128 v[172:175], v152 offset:3072
	ds_read_b128 v[176:179], v153
	ds_read_b128 v[180:183], v153 offset:1024
	ds_read_b128 v[184:187], v153 offset:2048
	ds_read_b128 v[188:191], v153 offset:3072
	s_add_i32 s25, s24, 2
	s_add_u32 s58, s56, 0xfff80080
	s_addc_u32 s59, s57, -1
	s_cmp_eq_u32 s82, s24
	s_cselect_b32 s61, s39, s59
	s_cselect_b32 s60, s49, s58
	s_cselect_b32 s59, s80, s84
	s_cselect_b32 s58, s81, s83
	s_cselect_b64 s[100:101], s[50:51], -1
	v_lshl_add_u64 v[150:151], s[56:57], 0, v[142:143]
	s_add_i32 m0, s62, 0xc000
	ds_read_b128 v[192:195], v154
	ds_read_b128 v[196:199], v154 offset:1024
	ds_read_b128 v[200:203], v154 offset:2048
	ds_read_b128 v[204:207], v154 offset:3072
	ds_read_b128 v[208:211], v154 offset:4096
	ds_read_b128 v[212:215], v154 offset:5120
	ds_read_b128 v[216:219], v154 offset:6144
	ds_read_b128 v[220:223], v154 offset:7168
	global_load_lds_dwordx4 v[150:151], off
	v_lshl_add_u64 v[150:151], s[56:57], 0, v[144:145]
	s_add_i32 m0, s62, 0xe000
	s_nop 0
	global_load_lds_dwordx4 v[150:151], off
	s_waitcnt vmcnt(8)
	s_waitcnt lgkmcnt(0)
	s_barrier
	s_waitcnt lgkmcnt(0)
	v_mfma_f32_16x16x32_bf16 v[106:109], v[156:159], v[192:195], v[106:109]
	v_mfma_f32_16x16x32_bf16 v[98:101], v[168:171], v[192:195], v[98:101]
	v_mfma_f32_16x16x32_bf16 v[90:93], v[156:159], v[200:203], v[90:93]
	v_mfma_f32_16x16x32_bf16 v[82:85], v[168:171], v[200:203], v[82:85]
	v_mfma_f32_16x16x32_bf16 v[70:73], v[156:159], v[208:211], v[70:73]
	v_mfma_f32_16x16x32_bf16 v[62:65], v[168:171], v[208:211], v[62:65]
	v_mfma_f32_16x16x32_bf16 v[46:49], v[156:159], v[216:219], v[46:49]
	v_mfma_f32_16x16x32_bf16 v[38:41], v[168:171], v[216:219], v[38:41]
	v_mfma_f32_16x16x32_bf16 v[106:109], v[164:167], v[196:199], v[106:109]
	v_mfma_f32_16x16x32_bf16 v[98:101], v[172:175], v[196:199], v[98:101]
	v_mfma_f32_16x16x32_bf16 v[90:93], v[164:167], v[204:207], v[90:93]
	v_mfma_f32_16x16x32_bf16 v[82:85], v[172:175], v[204:207], v[82:85]
	v_mfma_f32_16x16x32_bf16 v[70:73], v[164:167], v[212:215], v[70:73]
	v_mfma_f32_16x16x32_bf16 v[62:65], v[172:175], v[212:215], v[62:65]
	v_mfma_f32_16x16x32_bf16 v[46:49], v[164:167], v[220:223], v[46:49]
	v_mfma_f32_16x16x32_bf16 v[38:41], v[172:175], v[220:223], v[38:41]
	v_mfma_f32_16x16x32_bf16 v[66:69], v[176:179], v[192:195], v[66:69]
	v_mfma_f32_16x16x32_bf16 v[58:61], v[184:187], v[192:195], v[58:61]
	v_mfma_f32_16x16x32_bf16 v[42:45], v[176:179], v[200:203], v[42:45]
	v_mfma_f32_16x16x32_bf16 v[34:37], v[184:187], v[200:203], v[34:37]
	v_mfma_f32_16x16x32_bf16 v[22:25], v[176:179], v[208:211], v[22:25]
	v_mfma_f32_16x16x32_bf16 v[18:21], v[184:187], v[208:211], v[18:21]
	v_mfma_f32_16x16x32_bf16 v[14:17], v[176:179], v[216:219], v[14:17]
	v_mfma_f32_16x16x32_bf16 v[6:9], v[184:187], v[216:219], v[6:9]
	v_mfma_f32_16x16x32_bf16 v[66:69], v[180:183], v[196:199], v[66:69]
	v_mfma_f32_16x16x32_bf16 v[58:61], v[188:191], v[196:199], v[58:61]
	v_mfma_f32_16x16x32_bf16 v[42:45], v[180:183], v[204:207], v[42:45]
	v_mfma_f32_16x16x32_bf16 v[34:37], v[188:191], v[204:207], v[34:37]
	v_mfma_f32_16x16x32_bf16 v[22:25], v[180:183], v[212:215], v[22:25]
	v_mfma_f32_16x16x32_bf16 v[18:21], v[188:191], v[212:215], v[18:21]
	v_mfma_f32_16x16x32_bf16 v[14:17], v[180:183], v[220:223], v[14:17]
	v_mfma_f32_16x16x32_bf16 v[6:9], v[188:191], v[220:223], v[6:9]
	s_barrier
	s_add_i32 s24, s72, s31
	v_lshl_add_u64 v[150:151], s[58:59], 0, v[132:133]
	s_mov_b32 m0, s24
	ds_read_b128 v[192:195], v154 offset:16384
	ds_read_b128 v[196:199], v154 offset:17408
	ds_read_b128 v[200:203], v154 offset:18432
	ds_read_b128 v[204:207], v154 offset:19456
	ds_read_b128 v[208:211], v154 offset:20480
	ds_read_b128 v[212:215], v154 offset:21504
	ds_read_b128 v[216:219], v154 offset:22528
	ds_read_b128 v[220:223], v154 offset:23552
	s_mov_b64 exec, s[100:101]
	global_load_lds_dwordx4 v[150:151], off
	s_mov_b64 exec, -1
	s_add_i32 m0, s24, 0x2000
	s_add_u32 s86, s58, 0x80000
	v_lshl_add_u64 v[160:161], s[58:59], 0, v[136:137]
	s_addc_u32 s87, s59, 0
	s_add_i32 s24, s73, s31
	s_mov_b64 exec, s[100:101]
	global_load_lds_dwordx4 v[160:161], off
	s_mov_b64 exec, -1
	v_lshl_add_u64 v[224:225], s[86:87], 0, v[132:133]
	s_mov_b32 m0, s24
	v_lshl_add_u64 v[226:227], s[60:61], 0, v[134:135]
	s_mov_b64 exec, s[100:101]
	global_load_lds_dwordx4 v[224:225], off
	s_mov_b64 exec, -1
	v_lshl_add_u64 v[224:225], s[86:87], 0, v[136:137]
	s_add_i32 m0, s24, 0x2000
	s_nop 0
	s_mov_b64 exec, s[100:101]
	global_load_lds_dwordx4 v[224:225], off
	s_mov_b64 exec, -1
	v_lshl_add_u64 v[224:225], s[60:61], 0, v[130:131]
	s_mov_b32 m0, s62
	s_nop 0
	s_mov_b64 exec, s[100:101]
	global_load_lds_dwordx4 v[224:225], off
	s_mov_b64 exec, -1
	s_mov_b32 m0, s63
	s_nop 0
	s_mov_b64 exec, s[100:101]
	global_load_lds_dwordx4 v[226:227], off
	s_mov_b64 exec, -1
	s_waitcnt vmcnt(8)
	s_waitcnt lgkmcnt(0)
	s_barrier
	s_waitcnt lgkmcnt(0)
	v_mfma_f32_16x16x32_bf16 v[126:129], v[156:159], v[192:195], v[126:129]
	v_mfma_f32_16x16x32_bf16 v[122:125], v[168:171], v[192:195], v[122:125]
	v_mfma_f32_16x16x32_bf16 v[118:121], v[156:159], v[200:203], v[118:121]
	v_mfma_f32_16x16x32_bf16 v[114:117], v[168:171], v[200:203], v[114:117]
	v_mfma_f32_16x16x32_bf16 v[94:97], v[156:159], v[208:211], v[94:97]
	v_mfma_f32_16x16x32_bf16 v[86:89], v[168:171], v[208:211], v[86:89]
	v_mfma_f32_16x16x32_bf16 v[54:57], v[156:159], v[216:219], v[54:57]
	v_mfma_f32_16x16x32_bf16 v[50:53], v[168:171], v[216:219], v[50:53]
	v_mfma_f32_16x16x32_bf16 v[126:129], v[164:167], v[196:199], v[126:129]
	v_mfma_f32_16x16x32_bf16 v[122:125], v[172:175], v[196:199], v[122:125]
	v_mfma_f32_16x16x32_bf16 v[118:121], v[164:167], v[204:207], v[118:121]
	v_mfma_f32_16x16x32_bf16 v[114:117], v[172:175], v[204:207], v[114:117]
	v_mfma_f32_16x16x32_bf16 v[94:97], v[164:167], v[212:215], v[94:97]
	v_mfma_f32_16x16x32_bf16 v[86:89], v[172:175], v[212:215], v[86:89]
	v_mfma_f32_16x16x32_bf16 v[54:57], v[164:167], v[220:223], v[54:57]
	v_mfma_f32_16x16x32_bf16 v[50:53], v[172:175], v[220:223], v[50:53]
	v_mfma_f32_16x16x32_bf16 v[110:113], v[176:179], v[192:195], v[110:113]
	v_mfma_f32_16x16x32_bf16 v[102:105], v[184:187], v[192:195], v[102:105]
	v_mfma_f32_16x16x32_bf16 v[78:81], v[176:179], v[200:203], v[78:81]
	v_mfma_f32_16x16x32_bf16 v[74:77], v[184:187], v[200:203], v[74:77]
	v_mfma_f32_16x16x32_bf16 v[30:33], v[176:179], v[208:211], v[30:33]
	v_mfma_f32_16x16x32_bf16 v[26:29], v[184:187], v[208:211], v[26:29]
	v_mfma_f32_16x16x32_bf16 v[10:13], v[176:179], v[216:219], v[10:13]
	v_mfma_f32_16x16x32_bf16 v[2:5], v[184:187], v[216:219], v[2:5]
	v_mfma_f32_16x16x32_bf16 v[110:113], v[180:183], v[196:199], v[110:113]
	v_mfma_f32_16x16x32_bf16 v[102:105], v[188:191], v[196:199], v[102:105]
	v_mfma_f32_16x16x32_bf16 v[78:81], v[180:183], v[204:207], v[78:81]
	v_mfma_f32_16x16x32_bf16 v[74:77], v[188:191], v[204:207], v[74:77]
	v_mfma_f32_16x16x32_bf16 v[30:33], v[180:183], v[212:215], v[30:33]
	v_mfma_f32_16x16x32_bf16 v[26:29], v[188:191], v[212:215], v[26:29]
	v_mfma_f32_16x16x32_bf16 v[10:13], v[180:183], v[220:223], v[10:13]
	v_mfma_f32_16x16x32_bf16 v[2:5], v[188:191], v[220:223], v[2:5]
	s_barrier
	s_add_i32 s24, 0, 0x18000
	v_add_u32_e32 v155, s24, v1
	s_add_i32 s85, 0, 0x1c000
	ds_read_b128 v[156:159], v155
	ds_read_b128 v[164:167], v155 offset:1024
	ds_read_b128 v[168:171], v155 offset:2048
	ds_read_b128 v[172:175], v155 offset:3072
	v_add_u32_e32 v155, s85, v1
	ds_read_b128 v[176:179], v155
	ds_read_b128 v[180:183], v155 offset:1024
	ds_read_b128 v[184:187], v155 offset:2048
	ds_read_b128 v[188:191], v155 offset:3072
	s_add_u32 s60, s60, 0x80000
	s_addc_u32 s61, s61, 0
	s_mov_b32 m0, s64
	v_lshl_add_u64 v[228:229], s[60:61], 0, v[130:131]
	ds_read_b128 v[192:195], v154 offset:32768
	ds_read_b128 v[196:199], v154 offset:33792
	ds_read_b128 v[200:203], v154 offset:34816
	ds_read_b128 v[204:207], v154 offset:35840
	ds_read_b128 v[208:211], v154 offset:36864
	ds_read_b128 v[212:215], v154 offset:37888
	ds_read_b128 v[216:219], v154 offset:38912
	ds_read_b128 v[220:223], v154 offset:39936
	s_mov_b64 exec, s[100:101]
	global_load_lds_dwordx4 v[228:229], off
	s_mov_b64 exec, -1
	v_lshl_add_u64 v[228:229], s[60:61], 0, v[134:135]
	s_mov_b32 m0, s65
	s_nop 0
	s_mov_b64 exec, s[100:101]
	global_load_lds_dwordx4 v[228:229], off
	s_mov_b64 exec, -1
	s_waitcnt vmcnt(8)
	s_waitcnt lgkmcnt(0)
	s_barrier
	s_waitcnt lgkmcnt(0)
	v_mfma_f32_16x16x32_bf16 v[106:109], v[156:159], v[192:195], v[106:109]
	v_mfma_f32_16x16x32_bf16 v[98:101], v[168:171], v[192:195], v[98:101]
	v_mfma_f32_16x16x32_bf16 v[90:93], v[156:159], v[200:203], v[90:93]
	v_mfma_f32_16x16x32_bf16 v[82:85], v[168:171], v[200:203], v[82:85]
	v_mfma_f32_16x16x32_bf16 v[70:73], v[156:159], v[208:211], v[70:73]
	v_mfma_f32_16x16x32_bf16 v[62:65], v[168:171], v[208:211], v[62:65]
	v_mfma_f32_16x16x32_bf16 v[46:49], v[156:159], v[216:219], v[46:49]
	v_mfma_f32_16x16x32_bf16 v[38:41], v[168:171], v[216:219], v[38:41]
	v_mfma_f32_16x16x32_bf16 v[106:109], v[164:167], v[196:199], v[106:109]
	v_mfma_f32_16x16x32_bf16 v[98:101], v[172:175], v[196:199], v[98:101]
	v_mfma_f32_16x16x32_bf16 v[90:93], v[164:167], v[204:207], v[90:93]
	v_mfma_f32_16x16x32_bf16 v[82:85], v[172:175], v[204:207], v[82:85]
	v_mfma_f32_16x16x32_bf16 v[70:73], v[164:167], v[212:215], v[70:73]
	v_mfma_f32_16x16x32_bf16 v[62:65], v[172:175], v[212:215], v[62:65]
	v_mfma_f32_16x16x32_bf16 v[46:49], v[164:167], v[220:223], v[46:49]
	v_mfma_f32_16x16x32_bf16 v[38:41], v[172:175], v[220:223], v[38:41]
	v_mfma_f32_16x16x32_bf16 v[66:69], v[176:179], v[192:195], v[66:69]
	v_mfma_f32_16x16x32_bf16 v[58:61], v[184:187], v[192:195], v[58:61]
	v_mfma_f32_16x16x32_bf16 v[42:45], v[176:179], v[200:203], v[42:45]
	v_mfma_f32_16x16x32_bf16 v[34:37], v[184:187], v[200:203], v[34:37]
	v_mfma_f32_16x16x32_bf16 v[22:25], v[176:179], v[208:211], v[22:25]
	v_mfma_f32_16x16x32_bf16 v[18:21], v[184:187], v[208:211], v[18:21]
	v_mfma_f32_16x16x32_bf16 v[14:17], v[176:179], v[216:219], v[14:17]
	v_mfma_f32_16x16x32_bf16 v[6:9], v[184:187], v[216:219], v[6:9]
	v_mfma_f32_16x16x32_bf16 v[66:69], v[180:183], v[196:199], v[66:69]
	v_mfma_f32_16x16x32_bf16 v[58:61], v[188:191], v[196:199], v[58:61]
	v_mfma_f32_16x16x32_bf16 v[42:45], v[180:183], v[204:207], v[42:45]
	v_mfma_f32_16x16x32_bf16 v[34:37], v[188:191], v[204:207], v[34:37]
	v_mfma_f32_16x16x32_bf16 v[22:25], v[180:183], v[212:215], v[22:25]
	v_mfma_f32_16x16x32_bf16 v[18:21], v[188:191], v[212:215], v[18:21]
	v_mfma_f32_16x16x32_bf16 v[14:17], v[180:183], v[220:223], v[14:17]
	v_mfma_f32_16x16x32_bf16 v[6:9], v[188:191], v[220:223], v[6:9]
	s_barrier
	s_add_i32 s24, s24, s31
	v_lshl_add_u64 v[150:151], v[150:151], 0, s[12:13]
	s_mov_b32 m0, s24
	ds_read_b128 v[192:195], v154 offset:49152
	ds_read_b128 v[196:199], v154 offset:50176
	ds_read_b128 v[200:203], v154 offset:51200
	ds_read_b128 v[204:207], v154 offset:52224
	ds_read_b128 v[208:211], v154 offset:53248
	ds_read_b128 v[212:215], v154 offset:54272
	ds_read_b128 v[216:219], v154 offset:55296
	ds_read_b128 v[220:223], v154 offset:56320
	s_mov_b64 exec, s[100:101]
	global_load_lds_dwordx4 v[150:151], off
	s_mov_b64 exec, -1
	s_add_i32 m0, s24, 0x2000
	s_add_u32 s58, s58, 0x80080
	v_lshl_add_u64 v[150:151], v[160:161], 0, s[12:13]
	s_addc_u32 s59, s59, 0
	s_add_i32 s24, s85, s31
	s_mov_b64 exec, s[100:101]
	global_load_lds_dwordx4 v[150:151], off
	s_mov_b64 exec, -1
	v_lshl_add_u64 v[150:151], s[58:59], 0, v[132:133]
	s_mov_b32 m0, s24
	s_nop 0
	s_mov_b64 exec, s[100:101]
	global_load_lds_dwordx4 v[150:151], off
	s_mov_b64 exec, -1
	v_lshl_add_u64 v[150:151], s[58:59], 0, v[136:137]
	s_add_i32 m0, s24, 0x2000
	s_nop 0
	s_mov_b64 exec, s[100:101]
	global_load_lds_dwordx4 v[150:151], off
	s_mov_b64 exec, -1
	v_lshl_add_u64 v[150:151], v[224:225], 0, s[12:13]
	s_mov_b32 m0, s67
	s_nop 0
	s_mov_b64 exec, s[100:101]
	global_load_lds_dwordx4 v[150:151], off
	s_mov_b64 exec, -1
	v_lshl_add_u64 v[150:151], v[226:227], 0, s[12:13]
	s_mov_b32 m0, s68
	s_nop 0
	s_mov_b64 exec, s[100:101]
	global_load_lds_dwordx4 v[150:151], off
	s_mov_b64 exec, -1
	s_waitcnt vmcnt(8)
	s_waitcnt lgkmcnt(0)
	s_barrier
	s_waitcnt lgkmcnt(0)
	v_mfma_f32_16x16x32_bf16 v[126:129], v[156:159], v[192:195], v[126:129]
	v_mfma_f32_16x16x32_bf16 v[122:125], v[168:171], v[192:195], v[122:125]
	v_mfma_f32_16x16x32_bf16 v[118:121], v[156:159], v[200:203], v[118:121]
	v_mfma_f32_16x16x32_bf16 v[114:117], v[168:171], v[200:203], v[114:117]
	v_mfma_f32_16x16x32_bf16 v[94:97], v[156:159], v[208:211], v[94:97]
	v_mfma_f32_16x16x32_bf16 v[86:89], v[168:171], v[208:211], v[86:89]
	v_mfma_f32_16x16x32_bf16 v[54:57], v[156:159], v[216:219], v[54:57]
	v_mfma_f32_16x16x32_bf16 v[50:53], v[168:171], v[216:219], v[50:53]
	v_mfma_f32_16x16x32_bf16 v[126:129], v[164:167], v[196:199], v[126:129]
	v_mfma_f32_16x16x32_bf16 v[122:125], v[172:175], v[196:199], v[122:125]
	v_mfma_f32_16x16x32_bf16 v[118:121], v[164:167], v[204:207], v[118:121]
	v_mfma_f32_16x16x32_bf16 v[114:117], v[172:175], v[204:207], v[114:117]
	v_mfma_f32_16x16x32_bf16 v[94:97], v[164:167], v[212:215], v[94:97]
	v_mfma_f32_16x16x32_bf16 v[86:89], v[172:175], v[212:215], v[86:89]
	v_mfma_f32_16x16x32_bf16 v[54:57], v[164:167], v[220:223], v[54:57]
	v_mfma_f32_16x16x32_bf16 v[50:53], v[172:175], v[220:223], v[50:53]
	v_mfma_f32_16x16x32_bf16 v[110:113], v[176:179], v[192:195], v[110:113]
	v_mfma_f32_16x16x32_bf16 v[102:105], v[184:187], v[192:195], v[102:105]
	v_mfma_f32_16x16x32_bf16 v[78:81], v[176:179], v[200:203], v[78:81]
	v_mfma_f32_16x16x32_bf16 v[74:77], v[184:187], v[200:203], v[74:77]
	v_mfma_f32_16x16x32_bf16 v[30:33], v[176:179], v[208:211], v[30:33]
	v_mfma_f32_16x16x32_bf16 v[26:29], v[184:187], v[208:211], v[26:29]
	v_mfma_f32_16x16x32_bf16 v[10:13], v[176:179], v[216:219], v[10:13]
	v_mfma_f32_16x16x32_bf16 v[2:5], v[184:187], v[216:219], v[2:5]
	v_mfma_f32_16x16x32_bf16 v[110:113], v[180:183], v[196:199], v[110:113]
	v_mfma_f32_16x16x32_bf16 v[102:105], v[188:191], v[196:199], v[102:105]
	v_mfma_f32_16x16x32_bf16 v[78:81], v[180:183], v[204:207], v[78:81]
	v_mfma_f32_16x16x32_bf16 v[74:77], v[188:191], v[204:207], v[74:77]
	v_mfma_f32_16x16x32_bf16 v[30:33], v[180:183], v[212:215], v[30:33]
	v_mfma_f32_16x16x32_bf16 v[26:29], v[188:191], v[212:215], v[26:29]
	v_mfma_f32_16x16x32_bf16 v[10:13], v[180:183], v[220:223], v[10:13]
	v_mfma_f32_16x16x32_bf16 v[2:5], v[188:191], v[220:223], v[2:5]
	s_barrier
	s_add_u32 s56, s56, 0x100
	s_addc_u32 s57, s57, 0
	s_add_u32 s83, s83, 0x100
	s_addc_u32 s84, s84, 0
	s_cmp_ge_i32 s25, s78
	s_mov_b32 s24, s25
	s_cbranch_scc0 .LBB0_587
	s_and_b64 vcc, exec, s[14:15]
	s_cbranch_vccz .LBB0_592
	s_barrier
	s_mov_b64 s[56:57], -1
	s_cmp_lg_u32 s5, 1
	v_lshl_or_b32 v150, s71, 8, v139
	s_cbranch_scc1 .LBB0_593

.LBB0_995:
	ds_read_b128 v[148:151], v160
	ds_read_b128 v[152:155], v160 offset:1024
	ds_read_b128 v[164:167], v160 offset:2048
	ds_read_b128 v[168:171], v160 offset:3072
	ds_read_b128 v[172:175], v161
	ds_read_b128 v[176:179], v161 offset:1024
	ds_read_b128 v[180:183], v161 offset:2048
	ds_read_b128 v[184:187], v161 offset:3072
	s_add_i32 s25, s24, 2
	s_add_u32 s23, s48, 0xfff80080
	s_addc_u32 s35, s49, -1
	s_cmp_eq_u32 s75, s24
	s_cselect_b32 s53, s15, s35
	s_cselect_b32 s52, s31, s23
	s_cselect_b32 s51, s73, s77
	s_cselect_b32 s50, s74, s76
	s_cselect_b64 s[100:101], s[38:39], -1
	v_lshl_add_u64 v[156:157], s[48:49], 0, v[140:141]
	s_add_i32 m0, s55, 0xc000
	ds_read_b128 v[188:191], v163
	ds_read_b128 v[192:195], v163 offset:1024
	ds_read_b128 v[196:199], v163 offset:2048
	ds_read_b128 v[200:203], v163 offset:3072
	ds_read_b128 v[204:207], v163 offset:4096
	ds_read_b128 v[208:211], v163 offset:5120
	ds_read_b128 v[212:215], v163 offset:6144
	ds_read_b128 v[216:219], v163 offset:7168
	global_load_lds_dwordx4 v[156:157], off
	v_lshl_add_u64 v[156:157], s[48:49], 0, v[142:143]
	s_add_i32 m0, s55, 0xe000
	s_nop 0
	global_load_lds_dwordx4 v[156:157], off
	s_waitcnt vmcnt(8)
	s_waitcnt lgkmcnt(0)
	s_barrier
	s_waitcnt lgkmcnt(0)
	v_mfma_f32_16x16x32_bf16 v[78:81], v[148:151], v[188:191], v[78:81]
	v_mfma_f32_16x16x32_bf16 v[74:77], v[164:167], v[188:191], v[74:77]
	v_mfma_f32_16x16x32_bf16 v[70:73], v[148:151], v[196:199], v[70:73]
	v_mfma_f32_16x16x32_bf16 v[62:65], v[164:167], v[196:199], v[62:65]
	v_mfma_f32_16x16x32_bf16 v[54:57], v[148:151], v[204:207], v[54:57]
	v_mfma_f32_16x16x32_bf16 v[46:49], v[164:167], v[204:207], v[46:49]
	v_mfma_f32_16x16x32_bf16 v[38:41], v[148:151], v[212:215], v[38:41]
	v_mfma_f32_16x16x32_bf16 v[30:33], v[164:167], v[212:215], v[30:33]
	v_mfma_f32_16x16x32_bf16 v[78:81], v[152:155], v[192:195], v[78:81]
	v_mfma_f32_16x16x32_bf16 v[74:77], v[168:171], v[192:195], v[74:77]
	v_mfma_f32_16x16x32_bf16 v[70:73], v[152:155], v[200:203], v[70:73]
	v_mfma_f32_16x16x32_bf16 v[62:65], v[168:171], v[200:203], v[62:65]
	v_mfma_f32_16x16x32_bf16 v[54:57], v[152:155], v[208:211], v[54:57]
	v_mfma_f32_16x16x32_bf16 v[46:49], v[168:171], v[208:211], v[46:49]
	v_mfma_f32_16x16x32_bf16 v[38:41], v[152:155], v[216:219], v[38:41]
	v_mfma_f32_16x16x32_bf16 v[30:33], v[168:171], v[216:219], v[30:33]
	v_mfma_f32_16x16x32_bf16 v[50:53], v[172:175], v[188:191], v[50:53]
	v_mfma_f32_16x16x32_bf16 v[42:45], v[180:183], v[188:191], v[42:45]
	v_mfma_f32_16x16x32_bf16 v[34:37], v[172:175], v[196:199], v[34:37]
	v_mfma_f32_16x16x32_bf16 v[26:29], v[180:183], v[196:199], v[26:29]
	v_mfma_f32_16x16x32_bf16 v[22:25], v[172:175], v[204:207], v[22:25]
	v_mfma_f32_16x16x32_bf16 v[18:21], v[180:183], v[204:207], v[18:21]
	v_mfma_f32_16x16x32_bf16 v[10:13], v[172:175], v[212:215], v[10:13]
	v_mfma_f32_16x16x32_bf16 v[6:9], v[180:183], v[212:215], v[6:9]
	v_mfma_f32_16x16x32_bf16 v[50:53], v[176:179], v[192:195], v[50:53]
	v_mfma_f32_16x16x32_bf16 v[42:45], v[184:187], v[192:195], v[42:45]
	v_mfma_f32_16x16x32_bf16 v[34:37], v[176:179], v[200:203], v[34:37]
	v_mfma_f32_16x16x32_bf16 v[26:29], v[184:187], v[200:203], v[26:29]
	v_mfma_f32_16x16x32_bf16 v[22:25], v[176:179], v[208:211], v[22:25]
	v_mfma_f32_16x16x32_bf16 v[18:21], v[184:187], v[208:211], v[18:21]
	v_mfma_f32_16x16x32_bf16 v[10:13], v[176:179], v[216:219], v[10:13]
	v_mfma_f32_16x16x32_bf16 v[6:9], v[184:187], v[216:219], v[6:9]
	s_barrier
	s_add_i32 s23, s68, s54
	v_lshl_add_u64 v[156:157], s[50:51], 0, v[132:133]
	s_mov_b32 m0, s23
	ds_read_b128 v[188:191], v163 offset:16384
	ds_read_b128 v[192:195], v163 offset:17408
	ds_read_b128 v[196:199], v163 offset:18432
	ds_read_b128 v[200:203], v163 offset:19456
	ds_read_b128 v[204:207], v163 offset:20480
	ds_read_b128 v[208:211], v163 offset:21504
	ds_read_b128 v[212:215], v163 offset:22528
	ds_read_b128 v[216:219], v163 offset:23552
	s_mov_b64 exec, s[100:101]
	global_load_lds_dwordx4 v[156:157], off
	s_mov_b64 exec, -1
	s_add_i32 m0, s23, 0x2000
	s_add_u32 s78, s50, 0x80000
	v_lshl_add_u64 v[220:221], s[50:51], 0, v[136:137]
	s_addc_u32 s79, s51, 0
	s_add_i32 s23, s69, s54
	s_mov_b64 exec, s[100:101]
	global_load_lds_dwordx4 v[220:221], off
	s_mov_b64 exec, -1
	v_lshl_add_u64 v[222:223], s[78:79], 0, v[132:133]
	s_mov_b32 m0, s23
	v_lshl_add_u64 v[224:225], s[52:53], 0, v[134:135]
	s_mov_b64 exec, s[100:101]
	global_load_lds_dwordx4 v[222:223], off
	s_mov_b64 exec, -1
	v_lshl_add_u64 v[222:223], s[78:79], 0, v[136:137]
	s_add_i32 m0, s23, 0x2000
	s_nop 0
	s_mov_b64 exec, s[100:101]
	global_load_lds_dwordx4 v[222:223], off
	s_mov_b64 exec, -1
	v_lshl_add_u64 v[222:223], s[52:53], 0, v[130:131]
	s_mov_b32 m0, s55
	s_nop 0
	s_mov_b64 exec, s[100:101]
	global_load_lds_dwordx4 v[222:223], off
	s_mov_b64 exec, -1
	s_mov_b32 m0, s56
	s_nop 0
	s_mov_b64 exec, s[100:101]
	global_load_lds_dwordx4 v[224:225], off
	s_mov_b64 exec, -1
	s_waitcnt vmcnt(8)
	s_waitcnt lgkmcnt(0)
	s_barrier
	s_waitcnt lgkmcnt(0)
	v_mfma_f32_16x16x32_bf16 v[126:129], v[148:151], v[188:191], v[126:129]
	v_mfma_f32_16x16x32_bf16 v[122:125], v[164:167], v[188:191], v[122:125]
	v_mfma_f32_16x16x32_bf16 v[110:113], v[148:151], v[196:199], v[110:113]
	v_mfma_f32_16x16x32_bf16 v[106:109], v[164:167], v[196:199], v[106:109]
	v_mfma_f32_16x16x32_bf16 v[94:97], v[148:151], v[204:207], v[94:97]
	v_mfma_f32_16x16x32_bf16 v[90:93], v[164:167], v[204:207], v[90:93]
	v_mfma_f32_16x16x32_bf16 v[66:69], v[148:151], v[212:215], v[66:69]
	v_mfma_f32_16x16x32_bf16 v[58:61], v[164:167], v[212:215], v[58:61]
	v_mfma_f32_16x16x32_bf16 v[126:129], v[152:155], v[192:195], v[126:129]
	v_mfma_f32_16x16x32_bf16 v[122:125], v[168:171], v[192:195], v[122:125]
	v_mfma_f32_16x16x32_bf16 v[110:113], v[152:155], v[200:203], v[110:113]
	v_mfma_f32_16x16x32_bf16 v[106:109], v[168:171], v[200:203], v[106:109]
	v_mfma_f32_16x16x32_bf16 v[94:97], v[152:155], v[208:211], v[94:97]
	v_mfma_f32_16x16x32_bf16 v[90:93], v[168:171], v[208:211], v[90:93]
	v_mfma_f32_16x16x32_bf16 v[66:69], v[152:155], v[216:219], v[66:69]
	v_mfma_f32_16x16x32_bf16 v[58:61], v[168:171], v[216:219], v[58:61]
	v_mfma_f32_16x16x32_bf16 v[118:121], v[172:175], v[188:191], v[118:121]
	v_mfma_f32_16x16x32_bf16 v[114:117], v[180:183], v[188:191], v[114:117]
	v_mfma_f32_16x16x32_bf16 v[102:105], v[172:175], v[196:199], v[102:105]
	v_mfma_f32_16x16x32_bf16 v[98:101], v[180:183], v[196:199], v[98:101]
	v_mfma_f32_16x16x32_bf16 v[86:89], v[172:175], v[204:207], v[86:89]
	v_mfma_f32_16x16x32_bf16 v[82:85], v[180:183], v[204:207], v[82:85]
	v_mfma_f32_16x16x32_bf16 v[14:17], v[172:175], v[212:215], v[14:17]
	v_mfma_f32_16x16x32_bf16 v[2:5], v[180:183], v[212:215], v[2:5]
	v_mfma_f32_16x16x32_bf16 v[118:121], v[176:179], v[192:195], v[118:121]
	v_mfma_f32_16x16x32_bf16 v[114:117], v[184:187], v[192:195], v[114:117]
	v_mfma_f32_16x16x32_bf16 v[102:105], v[176:179], v[200:203], v[102:105]
	v_mfma_f32_16x16x32_bf16 v[98:101], v[184:187], v[200:203], v[98:101]
	v_mfma_f32_16x16x32_bf16 v[86:89], v[176:179], v[208:211], v[86:89]
	v_mfma_f32_16x16x32_bf16 v[82:85], v[184:187], v[208:211], v[82:85]
	v_mfma_f32_16x16x32_bf16 v[14:17], v[176:179], v[216:219], v[14:17]
	v_mfma_f32_16x16x32_bf16 v[2:5], v[184:187], v[216:219], v[2:5]
	s_barrier
	s_add_i32 s23, 0, 0x18000
	s_add_i32 s24, 0, 0x1c000
	v_add_u32_e32 v168, s23, v158
	v_add_u32_e32 v184, s24, v158
	ds_read_b128 v[148:151], v168
	ds_read_b128 v[152:155], v168 offset:1024
	ds_read_b128 v[164:167], v168 offset:2048
	ds_read_b128 v[168:171], v168 offset:3072
	ds_read_b128 v[172:175], v184
	ds_read_b128 v[176:179], v184 offset:1024
	ds_read_b128 v[180:183], v184 offset:2048
	ds_read_b128 v[184:187], v184 offset:3072
	s_add_u32 s52, s52, 0x80000
	s_addc_u32 s53, s53, 0
	s_mov_b32 m0, s57
	v_lshl_add_u64 v[226:227], s[52:53], 0, v[130:131]
	ds_read_b128 v[188:191], v163 offset:32768
	ds_read_b128 v[192:195], v163 offset:33792
	ds_read_b128 v[196:199], v163 offset:34816
	ds_read_b128 v[200:203], v163 offset:35840
	ds_read_b128 v[204:207], v163 offset:36864
	ds_read_b128 v[208:211], v163 offset:37888
	ds_read_b128 v[212:215], v163 offset:38912
	ds_read_b128 v[216:219], v163 offset:39936
	s_mov_b64 exec, s[100:101]
	global_load_lds_dwordx4 v[226:227], off
	s_mov_b64 exec, -1
	v_lshl_add_u64 v[226:227], s[52:53], 0, v[134:135]
	s_mov_b32 m0, s58
	s_nop 0
	s_mov_b64 exec, s[100:101]
	global_load_lds_dwordx4 v[226:227], off
	s_mov_b64 exec, -1
	s_waitcnt vmcnt(8)
	s_waitcnt lgkmcnt(0)
	s_barrier
	s_waitcnt lgkmcnt(0)
	v_mfma_f32_16x16x32_bf16 v[78:81], v[148:151], v[188:191], v[78:81]
	v_mfma_f32_16x16x32_bf16 v[74:77], v[164:167], v[188:191], v[74:77]
	v_mfma_f32_16x16x32_bf16 v[70:73], v[148:151], v[196:199], v[70:73]
	v_mfma_f32_16x16x32_bf16 v[62:65], v[164:167], v[196:199], v[62:65]
	v_mfma_f32_16x16x32_bf16 v[54:57], v[148:151], v[204:207], v[54:57]
	v_mfma_f32_16x16x32_bf16 v[46:49], v[164:167], v[204:207], v[46:49]
	v_mfma_f32_16x16x32_bf16 v[38:41], v[148:151], v[212:215], v[38:41]
	v_mfma_f32_16x16x32_bf16 v[30:33], v[164:167], v[212:215], v[30:33]
	v_mfma_f32_16x16x32_bf16 v[78:81], v[152:155], v[192:195], v[78:81]
	v_mfma_f32_16x16x32_bf16 v[74:77], v[168:171], v[192:195], v[74:77]
	v_mfma_f32_16x16x32_bf16 v[70:73], v[152:155], v[200:203], v[70:73]
	v_mfma_f32_16x16x32_bf16 v[62:65], v[168:171], v[200:203], v[62:65]
	v_mfma_f32_16x16x32_bf16 v[54:57], v[152:155], v[208:211], v[54:57]
	v_mfma_f32_16x16x32_bf16 v[46:49], v[168:171], v[208:211], v[46:49]
	v_mfma_f32_16x16x32_bf16 v[38:41], v[152:155], v[216:219], v[38:41]
	v_mfma_f32_16x16x32_bf16 v[30:33], v[168:171], v[216:219], v[30:33]
	v_mfma_f32_16x16x32_bf16 v[50:53], v[172:175], v[188:191], v[50:53]
	v_mfma_f32_16x16x32_bf16 v[42:45], v[180:183], v[188:191], v[42:45]
	v_mfma_f32_16x16x32_bf16 v[34:37], v[172:175], v[196:199], v[34:37]
	v_mfma_f32_16x16x32_bf16 v[26:29], v[180:183], v[196:199], v[26:29]
	v_mfma_f32_16x16x32_bf16 v[22:25], v[172:175], v[204:207], v[22:25]
	v_mfma_f32_16x16x32_bf16 v[18:21], v[180:183], v[204:207], v[18:21]
	v_mfma_f32_16x16x32_bf16 v[10:13], v[172:175], v[212:215], v[10:13]
	v_mfma_f32_16x16x32_bf16 v[6:9], v[180:183], v[212:215], v[6:9]
	v_mfma_f32_16x16x32_bf16 v[50:53], v[176:179], v[192:195], v[50:53]
	v_mfma_f32_16x16x32_bf16 v[42:45], v[184:187], v[192:195], v[42:45]
	v_mfma_f32_16x16x32_bf16 v[34:37], v[176:179], v[200:203], v[34:37]
	v_mfma_f32_16x16x32_bf16 v[26:29], v[184:187], v[200:203], v[26:29]
	v_mfma_f32_16x16x32_bf16 v[22:25], v[176:179], v[208:211], v[22:25]
	v_mfma_f32_16x16x32_bf16 v[18:21], v[184:187], v[208:211], v[18:21]
	v_mfma_f32_16x16x32_bf16 v[10:13], v[176:179], v[216:219], v[10:13]
	v_mfma_f32_16x16x32_bf16 v[6:9], v[184:187], v[216:219], v[6:9]
	s_barrier
	s_add_i32 s23, s23, s54
	v_lshl_add_u64 v[156:157], v[156:157], 0, s[8:9]
	s_mov_b32 m0, s23
	ds_read_b128 v[188:191], v163 offset:49152
	ds_read_b128 v[192:195], v163 offset:50176
	ds_read_b128 v[196:199], v163 offset:51200
	ds_read_b128 v[200:203], v163 offset:52224
	ds_read_b128 v[204:207], v163 offset:53248
	ds_read_b128 v[208:211], v163 offset:54272
	ds_read_b128 v[212:215], v163 offset:55296
	ds_read_b128 v[216:219], v163 offset:56320
	s_mov_b64 exec, s[100:101]
	global_load_lds_dwordx4 v[156:157], off
	s_mov_b64 exec, -1
	s_add_i32 m0, s23, 0x2000
	s_add_u32 s50, s50, 0x80080
	v_lshl_add_u64 v[156:157], v[220:221], 0, s[8:9]
	s_addc_u32 s51, s51, 0
	s_add_i32 s23, s24, s54
	s_mov_b64 exec, s[100:101]
	global_load_lds_dwordx4 v[156:157], off
	s_mov_b64 exec, -1
	v_lshl_add_u64 v[156:157], s[50:51], 0, v[132:133]
	s_mov_b32 m0, s23
	s_nop 0
	s_mov_b64 exec, s[100:101]
	global_load_lds_dwordx4 v[156:157], off
	s_mov_b64 exec, -1
	v_lshl_add_u64 v[156:157], s[50:51], 0, v[136:137]
	s_add_i32 m0, s23, 0x2000
	s_nop 0
	s_mov_b64 exec, s[100:101]
	global_load_lds_dwordx4 v[156:157], off
	s_mov_b64 exec, -1
	v_lshl_add_u64 v[156:157], v[222:223], 0, s[8:9]
	s_mov_b32 m0, s63
	s_nop 0
	s_mov_b64 exec, s[100:101]
	global_load_lds_dwordx4 v[156:157], off
	s_mov_b64 exec, -1
	v_lshl_add_u64 v[156:157], v[224:225], 0, s[8:9]
	s_mov_b32 m0, s64
	s_nop 0
	s_mov_b64 exec, s[100:101]
	global_load_lds_dwordx4 v[156:157], off
	s_mov_b64 exec, -1
	s_waitcnt vmcnt(8)
	s_waitcnt lgkmcnt(0)
	s_barrier
	s_waitcnt lgkmcnt(0)
	v_mfma_f32_16x16x32_bf16 v[126:129], v[148:151], v[188:191], v[126:129]
	v_mfma_f32_16x16x32_bf16 v[122:125], v[164:167], v[188:191], v[122:125]
	v_mfma_f32_16x16x32_bf16 v[110:113], v[148:151], v[196:199], v[110:113]
	v_mfma_f32_16x16x32_bf16 v[106:109], v[164:167], v[196:199], v[106:109]
	v_mfma_f32_16x16x32_bf16 v[94:97], v[148:151], v[204:207], v[94:97]
	v_mfma_f32_16x16x32_bf16 v[90:93], v[164:167], v[204:207], v[90:93]
	v_mfma_f32_16x16x32_bf16 v[66:69], v[148:151], v[212:215], v[66:69]
	v_mfma_f32_16x16x32_bf16 v[58:61], v[164:167], v[212:215], v[58:61]
	v_mfma_f32_16x16x32_bf16 v[126:129], v[152:155], v[192:195], v[126:129]
	v_mfma_f32_16x16x32_bf16 v[122:125], v[168:171], v[192:195], v[122:125]
	v_mfma_f32_16x16x32_bf16 v[110:113], v[152:155], v[200:203], v[110:113]
	v_mfma_f32_16x16x32_bf16 v[106:109], v[168:171], v[200:203], v[106:109]
	v_mfma_f32_16x16x32_bf16 v[94:97], v[152:155], v[208:211], v[94:97]
	v_mfma_f32_16x16x32_bf16 v[90:93], v[168:171], v[208:211], v[90:93]
	v_mfma_f32_16x16x32_bf16 v[66:69], v[152:155], v[216:219], v[66:69]
	v_mfma_f32_16x16x32_bf16 v[58:61], v[168:171], v[216:219], v[58:61]
	v_mfma_f32_16x16x32_bf16 v[118:121], v[172:175], v[188:191], v[118:121]
	v_mfma_f32_16x16x32_bf16 v[114:117], v[180:183], v[188:191], v[114:117]
	v_mfma_f32_16x16x32_bf16 v[102:105], v[172:175], v[196:199], v[102:105]
	v_mfma_f32_16x16x32_bf16 v[98:101], v[180:183], v[196:199], v[98:101]
	v_mfma_f32_16x16x32_bf16 v[86:89], v[172:175], v[204:207], v[86:89]
	v_mfma_f32_16x16x32_bf16 v[82:85], v[180:183], v[204:207], v[82:85]
	v_mfma_f32_16x16x32_bf16 v[14:17], v[172:175], v[212:215], v[14:17]
	v_mfma_f32_16x16x32_bf16 v[2:5], v[180:183], v[212:215], v[2:5]
	v_mfma_f32_16x16x32_bf16 v[118:121], v[176:179], v[192:195], v[118:121]
	v_mfma_f32_16x16x32_bf16 v[114:117], v[184:187], v[192:195], v[114:117]
	v_mfma_f32_16x16x32_bf16 v[102:105], v[176:179], v[200:203], v[102:105]
	v_mfma_f32_16x16x32_bf16 v[98:101], v[184:187], v[200:203], v[98:101]
	v_mfma_f32_16x16x32_bf16 v[86:89], v[176:179], v[208:211], v[86:89]
	v_mfma_f32_16x16x32_bf16 v[82:85], v[184:187], v[208:211], v[82:85]
	v_mfma_f32_16x16x32_bf16 v[14:17], v[176:179], v[216:219], v[14:17]
	v_mfma_f32_16x16x32_bf16 v[2:5], v[184:187], v[216:219], v[2:5]
	s_barrier
	s_add_u32 s48, s48, 0x100
	s_addc_u32 s49, s49, 0
	s_add_u32 s76, s76, 0x100
	s_addc_u32 s77, s77, 0
	s_cmp_ge_i32 s25, s72
	s_mov_b32 s24, s25
	s_cbranch_scc0 .LBB0_995
	s_and_b64 vcc, exec, s[10:11]
	s_cbranch_vccz .LBB0_998
	s_barrier

.LBB0_1248:
	ds_read_b128 v[146:149], v159
	ds_read_b128 v[150:153], v159 offset:1024
	ds_read_b128 v[164:167], v159 offset:2048
	ds_read_b128 v[168:171], v159 offset:3072
	ds_read_b128 v[172:175], v160
	ds_read_b128 v[176:179], v160 offset:1024
	ds_read_b128 v[180:183], v160 offset:2048
	ds_read_b128 v[184:187], v160 offset:3072
	s_add_i32 s25, s24, 2
	s_add_u32 s42, s38, 0xffea0080
	s_addc_u32 s43, s39, -1
	s_cmp_eq_u32 s70, s24
	s_cselect_b32 s45, s66, s43
	s_cselect_b32 s44, s67, s42
	s_cselect_b32 s43, s68, s72
	s_cselect_b32 s42, s69, s71
	s_cselect_b64 s[100:101], s[28:29], -1
	v_lshl_add_u64 v[154:155], s[38:39], 0, v[138:139]
	s_add_i32 m0, s33, 0xc000
	ds_read_b128 v[188:191], v161
	ds_read_b128 v[192:195], v161 offset:1024
	ds_read_b128 v[196:199], v161 offset:2048
	ds_read_b128 v[200:203], v161 offset:3072
	ds_read_b128 v[204:207], v161 offset:4096
	ds_read_b128 v[208:211], v161 offset:5120
	ds_read_b128 v[212:215], v161 offset:6144
	ds_read_b128 v[216:219], v161 offset:7168
	global_load_lds_dwordx4 v[154:155], off
	v_lshl_add_u64 v[154:155], s[38:39], 0, v[140:141]
	s_add_i32 m0, s33, 0xe000
	s_nop 0
	global_load_lds_dwordx4 v[154:155], off
	s_waitcnt vmcnt(8)
	s_waitcnt lgkmcnt(0)
	s_barrier
	s_waitcnt lgkmcnt(0)
	v_mfma_f32_16x16x32_bf16 v[76:79], v[146:149], v[188:191], v[76:79]
	v_mfma_f32_16x16x32_bf16 v[72:75], v[164:167], v[188:191], v[72:75]
	v_mfma_f32_16x16x32_bf16 v[64:67], v[146:149], v[196:199], v[64:67]
	v_mfma_f32_16x16x32_bf16 v[56:59], v[164:167], v[196:199], v[56:59]
	v_mfma_f32_16x16x32_bf16 v[52:55], v[146:149], v[204:207], v[52:55]
	v_mfma_f32_16x16x32_bf16 v[44:47], v[164:167], v[204:207], v[44:47]
	v_mfma_f32_16x16x32_bf16 v[36:39], v[146:149], v[212:215], v[36:39]
	v_mfma_f32_16x16x32_bf16 v[28:31], v[164:167], v[212:215], v[28:31]
	v_mfma_f32_16x16x32_bf16 v[76:79], v[150:153], v[192:195], v[76:79]
	v_mfma_f32_16x16x32_bf16 v[72:75], v[168:171], v[192:195], v[72:75]
	v_mfma_f32_16x16x32_bf16 v[64:67], v[150:153], v[200:203], v[64:67]
	v_mfma_f32_16x16x32_bf16 v[56:59], v[168:171], v[200:203], v[56:59]
	v_mfma_f32_16x16x32_bf16 v[52:55], v[150:153], v[208:211], v[52:55]
	v_mfma_f32_16x16x32_bf16 v[44:47], v[168:171], v[208:211], v[44:47]
	v_mfma_f32_16x16x32_bf16 v[36:39], v[150:153], v[216:219], v[36:39]
	v_mfma_f32_16x16x32_bf16 v[28:31], v[168:171], v[216:219], v[28:31]
	v_mfma_f32_16x16x32_bf16 v[48:51], v[172:175], v[188:191], v[48:51]
	v_mfma_f32_16x16x32_bf16 v[40:43], v[180:183], v[188:191], v[40:43]
	v_mfma_f32_16x16x32_bf16 v[32:35], v[172:175], v[196:199], v[32:35]
	v_mfma_f32_16x16x32_bf16 v[24:27], v[180:183], v[196:199], v[24:27]
	v_mfma_f32_16x16x32_bf16 v[20:23], v[172:175], v[204:207], v[20:23]
	v_mfma_f32_16x16x32_bf16 v[16:19], v[180:183], v[204:207], v[16:19]
	v_mfma_f32_16x16x32_bf16 v[8:11], v[172:175], v[212:215], v[8:11]
	v_mfma_f32_16x16x32_bf16 v[4:7], v[180:183], v[212:215], v[4:7]
	v_mfma_f32_16x16x32_bf16 v[48:51], v[176:179], v[192:195], v[48:51]
	v_mfma_f32_16x16x32_bf16 v[40:43], v[184:187], v[192:195], v[40:43]
	v_mfma_f32_16x16x32_bf16 v[32:35], v[176:179], v[200:203], v[32:35]
	v_mfma_f32_16x16x32_bf16 v[24:27], v[184:187], v[200:203], v[24:27]
	v_mfma_f32_16x16x32_bf16 v[20:23], v[176:179], v[208:211], v[20:23]
	v_mfma_f32_16x16x32_bf16 v[16:19], v[184:187], v[208:211], v[16:19]
	v_mfma_f32_16x16x32_bf16 v[8:11], v[176:179], v[216:219], v[8:11]
	v_mfma_f32_16x16x32_bf16 v[4:7], v[184:187], v[216:219], v[4:7]
	s_barrier
	s_add_i32 s24, s58, s23
	v_lshl_add_u64 v[154:155], s[42:43], 0, v[130:131]
	s_mov_b32 m0, s24
	ds_read_b128 v[188:191], v161 offset:16384
	ds_read_b128 v[192:195], v161 offset:17408
	ds_read_b128 v[196:199], v161 offset:18432
	ds_read_b128 v[200:203], v161 offset:19456
	ds_read_b128 v[204:207], v161 offset:20480
	ds_read_b128 v[208:211], v161 offset:21504
	ds_read_b128 v[212:215], v161 offset:22528
	ds_read_b128 v[216:219], v161 offset:23552
	s_mov_b64 exec, s[100:101]
	global_load_lds_dwordx4 v[154:155], off
	s_mov_b64 exec, -1
	s_add_i32 m0, s24, 0x2000
	s_add_u32 s74, s42, 0x160000
	v_lshl_add_u64 v[220:221], s[42:43], 0, v[134:135]
	s_addc_u32 s75, s43, 0
	s_add_i32 s24, s59, s23
	s_mov_b64 exec, s[100:101]
	global_load_lds_dwordx4 v[220:221], off
	s_mov_b64 exec, -1
	v_lshl_add_u64 v[222:223], s[74:75], 0, v[130:131]
	s_mov_b32 m0, s24
	v_lshl_add_u64 v[224:225], s[44:45], 0, v[132:133]
	s_mov_b64 exec, s[100:101]
	global_load_lds_dwordx4 v[222:223], off
	s_mov_b64 exec, -1
	v_lshl_add_u64 v[222:223], s[74:75], 0, v[134:135]
	s_add_i32 m0, s24, 0x2000
	s_nop 0
	s_mov_b64 exec, s[100:101]
	global_load_lds_dwordx4 v[222:223], off
	s_mov_b64 exec, -1
	v_lshl_add_u64 v[222:223], s[44:45], 0, v[128:129]
	s_mov_b32 m0, s33
	s_nop 0
	s_mov_b64 exec, s[100:101]
	global_load_lds_dwordx4 v[222:223], off
	s_mov_b64 exec, -1
	s_mov_b32 m0, s46
	s_nop 0
	s_mov_b64 exec, s[100:101]
	global_load_lds_dwordx4 v[224:225], off
	s_mov_b64 exec, -1
	s_waitcnt vmcnt(8)
	s_waitcnt lgkmcnt(0)
	s_barrier
	s_waitcnt lgkmcnt(0)
	v_mfma_f32_16x16x32_bf16 v[124:127], v[146:149], v[188:191], v[124:127]
	v_mfma_f32_16x16x32_bf16 v[120:123], v[164:167], v[188:191], v[120:123]
	v_mfma_f32_16x16x32_bf16 v[108:111], v[146:149], v[196:199], v[108:111]
	v_mfma_f32_16x16x32_bf16 v[104:107], v[164:167], v[196:199], v[104:107]
	v_mfma_f32_16x16x32_bf16 v[92:95], v[146:149], v[204:207], v[92:95]
	v_mfma_f32_16x16x32_bf16 v[88:91], v[164:167], v[204:207], v[88:91]
	v_mfma_f32_16x16x32_bf16 v[68:71], v[146:149], v[212:215], v[68:71]
	v_mfma_f32_16x16x32_bf16 v[60:63], v[164:167], v[212:215], v[60:63]
	v_mfma_f32_16x16x32_bf16 v[124:127], v[150:153], v[192:195], v[124:127]
	v_mfma_f32_16x16x32_bf16 v[120:123], v[168:171], v[192:195], v[120:123]
	v_mfma_f32_16x16x32_bf16 v[108:111], v[150:153], v[200:203], v[108:111]
	v_mfma_f32_16x16x32_bf16 v[104:107], v[168:171], v[200:203], v[104:107]
	v_mfma_f32_16x16x32_bf16 v[92:95], v[150:153], v[208:211], v[92:95]
	v_mfma_f32_16x16x32_bf16 v[88:91], v[168:171], v[208:211], v[88:91]
	v_mfma_f32_16x16x32_bf16 v[68:71], v[150:153], v[216:219], v[68:71]
	v_mfma_f32_16x16x32_bf16 v[60:63], v[168:171], v[216:219], v[60:63]
	v_mfma_f32_16x16x32_bf16 v[116:119], v[172:175], v[188:191], v[116:119]
	v_mfma_f32_16x16x32_bf16 v[112:115], v[180:183], v[188:191], v[112:115]
	v_mfma_f32_16x16x32_bf16 v[100:103], v[172:175], v[196:199], v[100:103]
	v_mfma_f32_16x16x32_bf16 v[96:99], v[180:183], v[196:199], v[96:99]
	v_mfma_f32_16x16x32_bf16 v[84:87], v[172:175], v[204:207], v[84:87]
	v_mfma_f32_16x16x32_bf16 v[80:83], v[180:183], v[204:207], v[80:83]
	v_mfma_f32_16x16x32_bf16 v[12:15], v[172:175], v[212:215], v[12:15]
	v_mfma_f32_16x16x32_bf16 v[0:3], v[180:183], v[212:215], v[0:3]
	v_mfma_f32_16x16x32_bf16 v[116:119], v[176:179], v[192:195], v[116:119]
	v_mfma_f32_16x16x32_bf16 v[112:115], v[184:187], v[192:195], v[112:115]
	v_mfma_f32_16x16x32_bf16 v[100:103], v[176:179], v[200:203], v[100:103]
	v_mfma_f32_16x16x32_bf16 v[96:99], v[184:187], v[200:203], v[96:99]
	v_mfma_f32_16x16x32_bf16 v[84:87], v[176:179], v[208:211], v[84:87]
	v_mfma_f32_16x16x32_bf16 v[80:83], v[184:187], v[208:211], v[80:83]
	v_mfma_f32_16x16x32_bf16 v[12:15], v[176:179], v[216:219], v[12:15]
	v_mfma_f32_16x16x32_bf16 v[0:3], v[184:187], v[216:219], v[0:3]
	s_barrier
	s_add_i32 s24, 0, 0x18000
	v_add_u32_e32 v163, s24, v157
	s_add_i32 s73, 0, 0x1c000
	ds_read_b128 v[146:149], v163
	ds_read_b128 v[150:153], v163 offset:1024
	ds_read_b128 v[164:167], v163 offset:2048
	ds_read_b128 v[168:171], v163 offset:3072
	v_add_u32_e32 v163, s73, v157
	ds_read_b128 v[172:175], v163
	ds_read_b128 v[176:179], v163 offset:1024
	ds_read_b128 v[180:183], v163 offset:2048
	ds_read_b128 v[184:187], v163 offset:3072
	s_add_u32 s44, s44, 0x160000
	s_addc_u32 s45, s45, 0
	s_mov_b32 m0, s47
	v_lshl_add_u64 v[226:227], s[44:45], 0, v[128:129]
	ds_read_b128 v[188:191], v161 offset:32768
	ds_read_b128 v[192:195], v161 offset:33792
	ds_read_b128 v[196:199], v161 offset:34816
	ds_read_b128 v[200:203], v161 offset:35840
	ds_read_b128 v[204:207], v161 offset:36864
	ds_read_b128 v[208:211], v161 offset:37888
	ds_read_b128 v[212:215], v161 offset:38912
	ds_read_b128 v[216:219], v161 offset:39936
	s_mov_b64 exec, s[100:101]
	global_load_lds_dwordx4 v[226:227], off
	s_mov_b64 exec, -1
	v_lshl_add_u64 v[226:227], s[44:45], 0, v[132:133]
	s_mov_b32 m0, s48
	s_nop 0
	s_mov_b64 exec, s[100:101]
	global_load_lds_dwordx4 v[226:227], off
	s_mov_b64 exec, -1
	s_waitcnt vmcnt(8)
	s_waitcnt lgkmcnt(0)
	s_barrier
	s_waitcnt lgkmcnt(0)
	v_mfma_f32_16x16x32_bf16 v[76:79], v[146:149], v[188:191], v[76:79]
	v_mfma_f32_16x16x32_bf16 v[72:75], v[164:167], v[188:191], v[72:75]
	v_mfma_f32_16x16x32_bf16 v[64:67], v[146:149], v[196:199], v[64:67]
	v_mfma_f32_16x16x32_bf16 v[56:59], v[164:167], v[196:199], v[56:59]
	v_mfma_f32_16x16x32_bf16 v[52:55], v[146:149], v[204:207], v[52:55]
	v_mfma_f32_16x16x32_bf16 v[44:47], v[164:167], v[204:207], v[44:47]
	v_mfma_f32_16x16x32_bf16 v[36:39], v[146:149], v[212:215], v[36:39]
	v_mfma_f32_16x16x32_bf16 v[28:31], v[164:167], v[212:215], v[28:31]
	v_mfma_f32_16x16x32_bf16 v[76:79], v[150:153], v[192:195], v[76:79]
	v_mfma_f32_16x16x32_bf16 v[72:75], v[168:171], v[192:195], v[72:75]
	v_mfma_f32_16x16x32_bf16 v[64:67], v[150:153], v[200:203], v[64:67]
	v_mfma_f32_16x16x32_bf16 v[56:59], v[168:171], v[200:203], v[56:59]
	v_mfma_f32_16x16x32_bf16 v[52:55], v[150:153], v[208:211], v[52:55]
	v_mfma_f32_16x16x32_bf16 v[44:47], v[168:171], v[208:211], v[44:47]
	v_mfma_f32_16x16x32_bf16 v[36:39], v[150:153], v[216:219], v[36:39]
	v_mfma_f32_16x16x32_bf16 v[28:31], v[168:171], v[216:219], v[28:31]
	v_mfma_f32_16x16x32_bf16 v[48:51], v[172:175], v[188:191], v[48:51]
	v_mfma_f32_16x16x32_bf16 v[40:43], v[180:183], v[188:191], v[40:43]
	v_mfma_f32_16x16x32_bf16 v[32:35], v[172:175], v[196:199], v[32:35]
	v_mfma_f32_16x16x32_bf16 v[24:27], v[180:183], v[196:199], v[24:27]
	v_mfma_f32_16x16x32_bf16 v[20:23], v[172:175], v[204:207], v[20:23]
	v_mfma_f32_16x16x32_bf16 v[16:19], v[180:183], v[204:207], v[16:19]
	v_mfma_f32_16x16x32_bf16 v[8:11], v[172:175], v[212:215], v[8:11]
	v_mfma_f32_16x16x32_bf16 v[4:7], v[180:183], v[212:215], v[4:7]
	v_mfma_f32_16x16x32_bf16 v[48:51], v[176:179], v[192:195], v[48:51]
	v_mfma_f32_16x16x32_bf16 v[40:43], v[184:187], v[192:195], v[40:43]
	v_mfma_f32_16x16x32_bf16 v[32:35], v[176:179], v[200:203], v[32:35]
	v_mfma_f32_16x16x32_bf16 v[24:27], v[184:187], v[200:203], v[24:27]
	v_mfma_f32_16x16x32_bf16 v[20:23], v[176:179], v[208:211], v[20:23]
	v_mfma_f32_16x16x32_bf16 v[16:19], v[184:187], v[208:211], v[16:19]
	v_mfma_f32_16x16x32_bf16 v[8:11], v[176:179], v[216:219], v[8:11]
	v_mfma_f32_16x16x32_bf16 v[4:7], v[184:187], v[216:219], v[4:7]
	s_barrier
	s_add_i32 s24, s24, s23
	v_lshl_add_u64 v[154:155], v[154:155], 0, s[8:9]
	s_mov_b32 m0, s24
	ds_read_b128 v[188:191], v161 offset:49152
	ds_read_b128 v[192:195], v161 offset:50176
	ds_read_b128 v[196:199], v161 offset:51200
	ds_read_b128 v[200:203], v161 offset:52224
	ds_read_b128 v[204:207], v161 offset:53248
	ds_read_b128 v[208:211], v161 offset:54272
	ds_read_b128 v[212:215], v161 offset:55296
	ds_read_b128 v[216:219], v161 offset:56320
	s_mov_b64 exec, s[100:101]
	global_load_lds_dwordx4 v[154:155], off
	s_mov_b64 exec, -1
	s_add_i32 m0, s24, 0x2000
	s_add_u32 s42, s42, 0x160080
	v_lshl_add_u64 v[154:155], v[220:221], 0, s[8:9]
	s_addc_u32 s43, s43, 0
	s_add_i32 s24, s73, s23
	s_mov_b64 exec, s[100:101]
	global_load_lds_dwordx4 v[154:155], off
	s_mov_b64 exec, -1
	v_lshl_add_u64 v[154:155], s[42:43], 0, v[130:131]
	s_mov_b32 m0, s24
	s_nop 0
	s_mov_b64 exec, s[100:101]
	global_load_lds_dwordx4 v[154:155], off
	s_mov_b64 exec, -1
	v_lshl_add_u64 v[154:155], s[42:43], 0, v[134:135]
	s_add_i32 m0, s24, 0x2000
	s_nop 0
	s_mov_b64 exec, s[100:101]
	global_load_lds_dwordx4 v[154:155], off
	s_mov_b64 exec, -1
	v_lshl_add_u64 v[154:155], v[222:223], 0, s[8:9]
	s_mov_b32 m0, s54
	s_nop 0
	s_mov_b64 exec, s[100:101]
	global_load_lds_dwordx4 v[154:155], off
	s_mov_b64 exec, -1
	v_lshl_add_u64 v[154:155], v[224:225], 0, s[8:9]
	s_mov_b32 m0, s55
	s_nop 0
	s_mov_b64 exec, s[100:101]
	global_load_lds_dwordx4 v[154:155], off
	s_mov_b64 exec, -1
	s_waitcnt vmcnt(8)
	s_waitcnt lgkmcnt(0)
	s_barrier
	s_waitcnt lgkmcnt(0)
	v_mfma_f32_16x16x32_bf16 v[124:127], v[146:149], v[188:191], v[124:127]
	v_mfma_f32_16x16x32_bf16 v[120:123], v[164:167], v[188:191], v[120:123]
	v_mfma_f32_16x16x32_bf16 v[108:111], v[146:149], v[196:199], v[108:111]
	v_mfma_f32_16x16x32_bf16 v[104:107], v[164:167], v[196:199], v[104:107]
	v_mfma_f32_16x16x32_bf16 v[92:95], v[146:149], v[204:207], v[92:95]
	v_mfma_f32_16x16x32_bf16 v[88:91], v[164:167], v[204:207], v[88:91]
	v_mfma_f32_16x16x32_bf16 v[68:71], v[146:149], v[212:215], v[68:71]
	v_mfma_f32_16x16x32_bf16 v[60:63], v[164:167], v[212:215], v[60:63]
	v_mfma_f32_16x16x32_bf16 v[124:127], v[150:153], v[192:195], v[124:127]
	v_mfma_f32_16x16x32_bf16 v[120:123], v[168:171], v[192:195], v[120:123]
	v_mfma_f32_16x16x32_bf16 v[108:111], v[150:153], v[200:203], v[108:111]
	v_mfma_f32_16x16x32_bf16 v[104:107], v[168:171], v[200:203], v[104:107]
	v_mfma_f32_16x16x32_bf16 v[92:95], v[150:153], v[208:211], v[92:95]
	v_mfma_f32_16x16x32_bf16 v[88:91], v[168:171], v[208:211], v[88:91]
	v_mfma_f32_16x16x32_bf16 v[68:71], v[150:153], v[216:219], v[68:71]
	v_mfma_f32_16x16x32_bf16 v[60:63], v[168:171], v[216:219], v[60:63]
	v_mfma_f32_16x16x32_bf16 v[116:119], v[172:175], v[188:191], v[116:119]
	v_mfma_f32_16x16x32_bf16 v[112:115], v[180:183], v[188:191], v[112:115]
	v_mfma_f32_16x16x32_bf16 v[100:103], v[172:175], v[196:199], v[100:103]
	v_mfma_f32_16x16x32_bf16 v[96:99], v[180:183], v[196:199], v[96:99]
	v_mfma_f32_16x16x32_bf16 v[84:87], v[172:175], v[204:207], v[84:87]
	v_mfma_f32_16x16x32_bf16 v[80:83], v[180:183], v[204:207], v[80:83]
	v_mfma_f32_16x16x32_bf16 v[12:15], v[172:175], v[212:215], v[12:15]
	v_mfma_f32_16x16x32_bf16 v[0:3], v[180:183], v[212:215], v[0:3]
	v_mfma_f32_16x16x32_bf16 v[116:119], v[176:179], v[192:195], v[116:119]
	v_mfma_f32_16x16x32_bf16 v[112:115], v[184:187], v[192:195], v[112:115]
	v_mfma_f32_16x16x32_bf16 v[100:103], v[176:179], v[200:203], v[100:103]
	v_mfma_f32_16x16x32_bf16 v[96:99], v[184:187], v[200:203], v[96:99]
	v_mfma_f32_16x16x32_bf16 v[84:87], v[176:179], v[208:211], v[84:87]
	v_mfma_f32_16x16x32_bf16 v[80:83], v[184:187], v[208:211], v[80:83]
	v_mfma_f32_16x16x32_bf16 v[12:15], v[176:179], v[216:219], v[12:15]
	v_mfma_f32_16x16x32_bf16 v[0:3], v[184:187], v[216:219], v[0:3]
	s_barrier
	s_add_u32 s38, s38, 0x100
	s_addc_u32 s39, s39, 0
	s_add_u32 s71, s71, 0x100
	s_addc_u32 s72, s72, 0
	s_cmp_ge_i32 s25, s65
	s_mov_b32 s24, s25
	s_cbranch_scc0 .LBB0_1248
	s_and_b64 vcc, exec, s[10:11]
	s_cbranch_vccz .LBB0_1251
	s_barrier
